# v164 with the P1 start stagger step raised from 35 to 45 sleep units
# baseline (speedup 1.0000x reference)
;     __host__ __device__ void init(int M, int N, int G_, int c_) { base.init(M, N, G_, c_); }
; __global__ void __launch_bounds__(512) mk_fwd(Args a) {
;     ...
;         pg8::Gemm g{(const bf16_t*)a.out, (const bf16_t*)(ws + WS_WIN), M_TOK, NPROJ, 1024}; pg8::StaticOrder S; S.init(M_TOK, NPROJ, G, blk);
;         pg8::EpiProj E{ws};
;         for (int rep = 0; rep < REP_P1; ++rep)
;         pg8::gemm_phase<pg8::EpiProj, pg8::StaticOrder, true, true>(lds, g, S, E);
.Lstg1_loop:
	s_sleep 45
	s_sub_u32 s98, s98, 1
	s_cmp_lg_u32 s98, 0
	s_cbranch_scc1 .Lstg1_loop
